# c53 + GLA step f ring buffer (3 exposed LDS waits instead of 12), G1 loop offset restored by dropping one pad nop
# baseline (speedup 1.0000x reference)
; DI void tok0_gemv(ldsp lds, const float* src, size_t sstride, const float* nw, const float* W, int N, float* Y, int ldy, const float* resid, size_t rstride, int task, int tid, int wid, int lane) {
;     ...
;     {
;         float4 v[4][4];
; #pragma unroll
;         for (int q = 0; q < 4; ++q) { const float* xr = src + (size_t)(wid + 8 * q) * sstride;
; #pragma unroll
;             for (int i = 0; i < 4; ++i) v[q][i] = *(const float4*)(xr + i * 256 + lane * 4); }
; __global__ void __launch_bounds__(NTHREADS, 2) megak(Params p) {
;     ...
;                 if (L == 0) for (int t = blockIdx.x; t < 32; t += gridDim.x)
;                     tok0_gemv(lds, T0BR, 1024, nullptr, p.w_out, 1024, T0X1, 1024, p.x, (size_t)SEQ * 1024, t, tid, wid, lane);
.LBB0_514:
	s_nop 0
	s_nop 0
	s_nop 0
	s_nop 0
	s_nop 0
	s_nop 0
	s_nop 0
	s_nop 0
	s_nop 0
	s_nop 0
	s_nop 0
	s_nop 0
	s_nop 0
	v_readlane_b32 s14, v252, 14
	v_readlane_b32 s22, v255, 7
	v_readlane_b32 s15, v252, 15
	v_readlane_b32 s23, v255, 8
	s_or_b64 s[14:15], s[22:23], s[14:15]
	s_and_b64 vcc, exec, s[14:15]
	s_cbranch_vccnz .LBB0_652
	v_readlane_b32 s14, v251, 27
	s_waitcnt vmcnt(0)
	v_lshlrev_b32_e32 v8, 4, v238
	v_mov_b32_e32 v9, v12
	v_readlane_b32 s15, v251, 28
	s_ashr_i32 s17, s16, 31
	v_lshrrev_b32_e32 v18, 5, v238
	v_lshl_add_u64 v[0:1], s[14:15], 0, v[8:9]
	s_lshl_b64 s[14:15], s[16:17], 12
	v_lshl_add_u64 v[0:1], v[0:1], 0, s[14:15]
	s_mov_b64 s[14:15], 0x8000
	v_lshl_add_u64 v[2:3], v[0:1], 0, s[14:15]
	s_mov_b64 s[14:15], 0x10000
	v_lshl_add_u64 v[4:5], v[0:1], 0, s[14:15]
	s_lshl_b32 s15, s16, 7
	v_lshl_or_b32 v14, v18, 2, s15
	v_or_b32_e32 v16, 2, v14
	v_ashrrev_i32_e32 v17, 31, v16
	v_lshlrev_b64 v[30:31], 12, v[16:17]
	v_or_b32_e32 v16, 3, v14
	v_ashrrev_i32_e32 v17, 31, v16
	v_lshlrev_b64 v[34:35], 12, v[16:17]
	v_or_b32_e32 v16, 8, v14
	v_ashrrev_i32_e32 v17, 31, v16
	v_lshlrev_b64 v[36:37], 12, v[16:17]
	v_or_b32_e32 v16, 9, v14
	v_ashrrev_i32_e32 v17, 31, v16
	s_waitcnt lgkmcnt(0)
; DI void tok0_gemv(ldsp lds, const float* src, size_t sstride, const float* nw, const float* W, int N, float* Y, int ldy, const float* resid, size_t rstride, int task, int tid, int wid, int lane) {
;     ...
;     const int c0 = task * 32, l31 = lane & 31, kk = lane >> 5, col = c0 + l31; const bool cv = col < N;
;     const int kb = wid * 128;
;     float wv[64];
; #pragma unroll
;     for (int q = 0; q < 16; ++q)
; #pragma unroll
;         for (int e = 0; e < 4; ++e) wv[q * 4 + e] = cv ? W[(size_t)(kb + 8 * q + 4 * kk + e) * N + col] : 0.f;
	v_lshlrev_b64 v[38:39], 12, v[16:17]
	v_or_b32_e32 v16, 10, v14
	v_ashrrev_i32_e32 v17, 31, v16
	v_lshlrev_b64 v[40:41], 12, v[16:17]
	v_or_b32_e32 v16, 11, v14
	v_ashrrev_i32_e32 v17, 31, v16
	v_lshlrev_b64 v[42:43], 12, v[16:17]
	v_or_b32_e32 v16, 16, v14
	v_ashrrev_i32_e32 v17, 31, v16
	v_lshlrev_b64 v[44:45], 12, v[16:17]
	v_or_b32_e32 v16, 17, v14
	v_ashrrev_i32_e32 v17, 31, v16
	v_lshlrev_b64 v[46:47], 12, v[16:17]
	v_or_b32_e32 v16, 18, v14
	v_ashrrev_i32_e32 v17, 31, v16
	v_lshlrev_b64 v[48:49], 12, v[16:17]
	v_or_b32_e32 v16, 19, v14
	v_ashrrev_i32_e32 v17, 31, v16
	v_lshlrev_b64 v[50:51], 12, v[16:17]
	v_or_b32_e32 v16, 24, v14
	v_ashrrev_i32_e32 v17, 31, v16
	v_lshlrev_b64 v[52:53], 12, v[16:17]
	v_or_b32_e32 v16, 25, v14
	v_ashrrev_i32_e32 v17, 31, v16
	v_lshlrev_b64 v[54:55], 12, v[16:17]
	v_or_b32_e32 v16, 26, v14
	v_ashrrev_i32_e32 v17, 31, v16
	v_lshlrev_b64 v[56:57], 12, v[16:17]
	v_or_b32_e32 v16, 27, v14
	v_ashrrev_i32_e32 v17, 31, v16
	v_lshlrev_b64 v[58:59], 12, v[16:17]
	v_or_b32_e32 v16, 32, v14
	v_ashrrev_i32_e32 v17, 31, v16
	v_lshlrev_b64 v[60:61], 12, v[16:17]
	v_or_b32_e32 v16, 33, v14
	v_ashrrev_i32_e32 v17, 31, v16
	v_lshlrev_b64 v[62:63], 12, v[16:17]
	v_or_b32_e32 v16, 34, v14
	v_ashrrev_i32_e32 v17, 31, v16
	v_lshlrev_b64 v[64:65], 12, v[16:17]
	v_or_b32_e32 v16, 35, v14
	v_ashrrev_i32_e32 v17, 31, v16
	v_lshlrev_b64 v[66:67], 12, v[16:17]
	v_or_b32_e32 v16, 40, v14
	v_ashrrev_i32_e32 v17, 31, v16
	v_lshlrev_b64 v[68:69], 12, v[16:17]
	v_or_b32_e32 v16, 41, v14
	v_ashrrev_i32_e32 v17, 31, v16
	v_lshlrev_b64 v[70:71], 12, v[16:17]
	v_or_b32_e32 v16, 42, v14
	v_ashrrev_i32_e32 v17, 31, v16
	v_lshlrev_b64 v[72:73], 12, v[16:17]
	v_or_b32_e32 v16, 43, v14
	v_ashrrev_i32_e32 v17, 31, v16
	v_lshlrev_b64 v[74:75], 12, v[16:17]
	v_or_b32_e32 v16, 48, v14
	v_ashrrev_i32_e32 v17, 31, v16
	v_lshlrev_b64 v[76:77], 12, v[16:17]
	v_or_b32_e32 v16, 49, v14
	v_ashrrev_i32_e32 v17, 31, v16
	v_lshlrev_b64 v[78:79], 12, v[16:17]
	v_or_b32_e32 v16, 50, v14
	v_ashrrev_i32_e32 v17, 31, v16
	v_lshlrev_b64 v[80:81], 12, v[16:17]
	v_or_b32_e32 v16, 51, v14
	v_ashrrev_i32_e32 v17, 31, v16
	v_lshlrev_b64 v[82:83], 12, v[16:17]
	v_or_b32_e32 v16, 56, v14
	v_ashrrev_i32_e32 v17, 31, v16
	v_lshlrev_b64 v[84:85], 12, v[16:17]
	v_or_b32_e32 v16, 57, v14
	v_ashrrev_i32_e32 v17, 31, v16
	v_lshlrev_b64 v[86:87], 12, v[16:17]
	v_or_b32_e32 v16, 58, v14
	v_ashrrev_i32_e32 v17, 31, v16
	v_lshlrev_b64 v[88:89], 12, v[16:17]
	v_or_b32_e32 v16, 59, v14
	v_ashrrev_i32_e32 v17, 31, v16
	v_lshlrev_b64 v[90:91], 12, v[16:17]
	v_or_b32_e32 v16, 64, v14
	v_ashrrev_i32_e32 v17, 31, v16
	v_lshlrev_b64 v[92:93], 12, v[16:17]
	v_or_b32_e32 v16, 0x41, v14
	v_ashrrev_i32_e32 v17, 31, v16
	v_lshlrev_b64 v[94:95], 12, v[16:17]
	v_or_b32_e32 v16, 0x42, v14
	v_ashrrev_i32_e32 v17, 31, v16
	v_lshlrev_b64 v[96:97], 12, v[16:17]
	v_or_b32_e32 v16, 0x43, v14
	v_ashrrev_i32_e32 v17, 31, v16
	v_lshlrev_b64 v[98:99], 12, v[16:17]
	v_or_b32_e32 v16, 0x48, v14
	v_ashrrev_i32_e32 v17, 31, v16
	v_lshlrev_b64 v[100:101], 12, v[16:17]
	v_or_b32_e32 v16, 0x49, v14
	v_ashrrev_i32_e32 v17, 31, v16
	v_lshlrev_b64 v[102:103], 12, v[16:17]
	v_or_b32_e32 v16, 0x4a, v14
	v_ashrrev_i32_e32 v17, 31, v16
	v_lshlrev_b64 v[104:105], 12, v[16:17]
	v_or_b32_e32 v16, 0x4b, v14
	v_ashrrev_i32_e32 v17, 31, v16
	v_lshlrev_b64 v[106:107], 12, v[16:17]
	v_or_b32_e32 v16, 0x50, v14
	v_ashrrev_i32_e32 v17, 31, v16
	v_lshlrev_b64 v[108:109], 12, v[16:17]
	v_or_b32_e32 v16, 0x51, v14
	v_ashrrev_i32_e32 v17, 31, v16
	v_lshlrev_b64 v[110:111], 12, v[16:17]
	v_or_b32_e32 v16, 0x52, v14
	v_ashrrev_i32_e32 v17, 31, v16
	v_lshlrev_b64 v[112:113], 12, v[16:17]
	v_or_b32_e32 v16, 0x53, v14
	v_ashrrev_i32_e32 v17, 31, v16
	v_lshlrev_b64 v[114:115], 12, v[16:17]
	v_or_b32_e32 v16, 0x58, v14
	v_ashrrev_i32_e32 v17, 31, v16
	v_lshlrev_b64 v[116:117], 12, v[16:17]
	v_or_b32_e32 v16, 0x59, v14
	v_ashrrev_i32_e32 v17, 31, v16
	v_lshlrev_b64 v[118:119], 12, v[16:17]
	v_or_b32_e32 v16, 0x5a, v14
	v_ashrrev_i32_e32 v17, 31, v16
	v_lshlrev_b64 v[120:121], 12, v[16:17]
	v_or_b32_e32 v16, 0x5b, v14
	v_ashrrev_i32_e32 v17, 31, v16
	v_lshlrev_b64 v[122:123], 12, v[16:17]
	v_or_b32_e32 v16, 0x60, v14
	v_ashrrev_i32_e32 v17, 31, v16
	v_lshlrev_b64 v[124:125], 12, v[16:17]
	v_or_b32_e32 v16, 0x61, v14
	v_ashrrev_i32_e32 v17, 31, v16
	v_lshlrev_b64 v[126:127], 12, v[16:17]
	v_or_b32_e32 v16, 0x62, v14
	v_ashrrev_i32_e32 v17, 31, v16
	v_lshlrev_b64 v[128:129], 12, v[16:17]
	v_or_b32_e32 v16, 0x63, v14
	v_ashrrev_i32_e32 v17, 31, v16
	v_lshlrev_b64 v[130:131], 12, v[16:17]
	v_or_b32_e32 v16, 0x68, v14
	v_ashrrev_i32_e32 v17, 31, v16
	v_lshlrev_b64 v[132:133], 12, v[16:17]
	v_or_b32_e32 v16, 0x69, v14
	v_ashrrev_i32_e32 v17, 31, v16
	v_lshlrev_b64 v[134:135], 12, v[16:17]
	v_or_b32_e32 v16, 0x6a, v14
	v_ashrrev_i32_e32 v17, 31, v16
	v_lshlrev_b64 v[136:137], 12, v[16:17]
	v_or_b32_e32 v16, 0x6b, v14
	v_ashrrev_i32_e32 v17, 31, v16
	v_lshlrev_b64 v[138:139], 12, v[16:17]
	v_or_b32_e32 v16, 0x70, v14
	v_ashrrev_i32_e32 v17, 31, v16
	v_lshlrev_b64 v[140:141], 12, v[16:17]
	v_or_b32_e32 v16, 0x71, v14
	v_ashrrev_i32_e32 v17, 31, v16
	v_lshlrev_b64 v[142:143], 12, v[16:17]
	v_or_b32_e32 v16, 0x72, v14
	v_ashrrev_i32_e32 v17, 31, v16
	v_lshlrev_b64 v[144:145], 12, v[16:17]
	v_or_b32_e32 v16, 0x73, v14
	v_ashrrev_i32_e32 v17, 31, v16
	v_lshlrev_b64 v[146:147], 12, v[16:17]
	v_or_b32_e32 v16, 0x78, v14
	v_ashrrev_i32_e32 v17, 31, v16
	v_lshlrev_b64 v[148:149], 12, v[16:17]
	v_or_b32_e32 v16, 0x79, v14
	v_ashrrev_i32_e32 v15, 31, v14
	v_ashrrev_i32_e32 v17, 31, v16
	v_add_u32_e32 v13, 0, v8
	v_lshlrev_b64 v[8:9], 12, v[14:15]
	v_or_b32_e32 v10, 1, v14
	v_lshlrev_b64 v[150:151], 12, v[16:17]
	v_or_b32_e32 v16, 0x7a, v14
	v_or_b32_e32 v14, 0x7b, v14
	v_and_b32_e32 v33, 31, v32
	v_ashrrev_i32_e32 v15, 31, v14
	s_movk_i32 s15, 0x1010
	v_ashrrev_i32_e32 v17, 31, v16
	v_lshlrev_b64 v[162:163], 12, v[14:15]
	v_mad_u32_u24 v14, v33, s15, 0
	s_lshl_b32 s15, s16, 12
	v_lshlrev_b64 v[152:153], 12, v[16:17]
	v_lshlrev_b32_e32 v16, 4, v18
	s_add_i32 s15, s15, 0
	v_lshlrev_b32_e32 v17, 9, v18
	v_lshlrev_b32_e32 v18, 2, v33
	v_add3_u32 v155, s15, v17, v18
	s_movk_i32 s15, 0x400
	s_mul_i32 s0, s16, 0x1010
	v_ashrrev_i32_e32 v11, 31, v10
	v_lshl_add_u32 v15, s16, 9, v14
	v_cmp_gt_i32_e64 s[38:39], s15, v32
	s_movk_i32 s15, 0xeff4
	v_lshl_add_u64 v[6:7], v[0:1], 0, s[28:29]
	s_add_i32 s14, s0, 0x10100
	v_lshlrev_b64 v[10:11], 12, v[10:11]
	v_mad_i32_i24 v156, v33, s15, v14
	v_add_u32_e32 v166, v15, v16
	s_mov_b32 s15, s78
	s_branch .LBB0_517
